# attention: exact two-pass softmax (all 5 key tiles' scores held in registers, ALiBi bias fed as MFMA C-input, no per-tile rescale); removed false store-drain waits
# speedup vs baseline: 1.0031x; 1.0031x over previous
.LBB0_420:
	s_add_i32 s7, s89, 1
	v_cvt_f32_i32_e32 v1, s7
	s_sub_i32 s7, 0x80, s69
	v_add_u32_e32 v253, s7, v188
	v_mul_f32_e32 v1, 0xc1000000, v1
	v_div_scale_f32 v2, s[8:9], s34, s34, v1
	v_rcp_f32_e32 v3, v2
	v_div_scale_f32 v4, vcc, v1, s34, v1
	s_mov_b32 s8, 0xc2fc0000
	v_fma_f32 v5, -v2, v3, 1.0
	v_fmac_f32_e32 v3, v5, v3
	v_mul_f32_e32 v5, v4, v3
	v_fma_f32 v6, -v2, v5, v4
	v_fmac_f32_e32 v5, v6, v3
	v_fma_f32 v2, -v2, v5, v4
	v_div_fmas_f32 v2, v2, v3, v5
	v_div_fixup_f32 v1, v2, s34, v1
	v_cmp_gt_f32_e32 vcc, s8, v1
	s_and_b64 s[8:9], vcc, exec
	s_cselect_b32 s8, 0xffffffc0, 0
	v_cndmask_b32_e32 v2, 0, v198, vcc
	v_add_f32_e32 v1, v1, v2
	v_exp_f32_e32 v1, v1
	v_cvt_f32_u32_e32 v2, s1
	v_and_b32_e32 v3, 64, v199
	v_add_u32_e32 v3, 64, v3
	v_ldexp_f32 v1, v1, s8
	v_mul_f32_e32 v1, v1, v2
	v_xor_b32_e32 v2, 32, v199
	v_mul_f32_e32 v91, 0x3fb8aa3b, v1
	v_add_u32_e32 v1, s13, v189
	v_cmp_lt_i32_e32 vcc, v2, v3
	v_subrev_u32_e32 v1, s97, v1
	v_mad_u32_u24 v252, v1, s83, v138
	v_cndmask_b32_e32 v2, v199, v2, vcc
	v_add_u32_e32 v1, s13, v190
	v_lshlrev_b32_e32 v141, 2, v2
	v_subrev_u32_e32 v1, s97, v1
	v_mad_u32_u24 v202, v1, s83, v132
	v_add_u32_e32 v252, 0xd800, v252
	s_add_i32 s14, s13, 0xffffff80
	ds_read_b128 v[0:3], v202
	ds_read_b128 v[4:7], v202 offset:32
	ds_read_b128 v[8:11], v202 offset:64
	ds_read_b128 v[12:15], v202 offset:96
	ds_read_b128 v[16:19], v202 offset:4608
	ds_read_b128 v[20:23], v202 offset:4640
	ds_read_b128 v[24:27], v202 offset:4672
	ds_read_b128 v[28:31], v202 offset:4704
	v_add_u32_e32 v174, 0x80, v188
	v_cvt_f32_i32_e32 v174, v174
	v_mul_f32_e64 v174, -v91, v174
	v_mul_f32_e32 v203, 0x42000000, v91
	v_fmamk_f32 v236, v91, 0x00000000, v174
	v_fmamk_f32 v237, v91, 0x3f800000, v174
	v_fmamk_f32 v238, v91, 0x40000000, v174
	v_fmamk_f32 v239, v91, 0x40400000, v174
	v_fmamk_f32 v240, v91, 0x40800000, v174
	v_fmamk_f32 v241, v91, 0x40a00000, v174
	v_fmamk_f32 v242, v91, 0x40c00000, v174
	v_fmamk_f32 v243, v91, 0x40e00000, v174
	v_fmamk_f32 v244, v91, 0x41800000, v174
	v_fmamk_f32 v245, v91, 0x41880000, v174
	v_fmamk_f32 v246, v91, 0x41900000, v174
	v_fmamk_f32 v247, v91, 0x41980000, v174
	v_fmamk_f32 v248, v91, 0x41a00000, v174
	v_fmamk_f32 v249, v91, 0x41a80000, v174
	v_fmamk_f32 v250, v91, 0x41b00000, v174
	v_fmamk_f32 v251, v91, 0x41b80000, v174
	s_nop 1
	s_waitcnt lgkmcnt(7)
	v_mfma_f32_32x32x16_bf16 v[32:47], v[0:3], v[48:51], v[236:251]
	s_waitcnt lgkmcnt(6)
	v_mfma_f32_32x32x16_bf16 v[32:47], v[4:7], v[52:55], v[32:47]
	s_waitcnt lgkmcnt(5)
	v_mfma_f32_32x32x16_bf16 v[32:47], v[8:11], v[56:59], v[32:47]
	s_waitcnt lgkmcnt(4)
	v_mfma_f32_32x32x16_bf16 v[32:47], v[12:15], v[60:63], v[32:47]
	ds_read_b128 v[0:3], v202 offset:9216
	ds_read_b128 v[4:7], v202 offset:9248
	ds_read_b128 v[8:11], v202 offset:9280
	ds_read_b128 v[12:15], v202 offset:9312
	s_waitcnt lgkmcnt(7)
	v_mfma_f32_32x32x16_bf16 v[142:157], v[16:19], v[48:51], v[236:251]
	s_waitcnt lgkmcnt(6)
	v_mfma_f32_32x32x16_bf16 v[142:157], v[20:23], v[52:55], v[142:157]
	s_waitcnt lgkmcnt(5)
	v_mfma_f32_32x32x16_bf16 v[142:157], v[24:27], v[56:59], v[142:157]
	s_waitcnt lgkmcnt(4)
	v_mfma_f32_32x32x16_bf16 v[142:157], v[28:31], v[60:63], v[142:157]
	ds_read_b128 v[16:19], v202 offset:13824
	ds_read_b128 v[20:23], v202 offset:13856
	ds_read_b128 v[24:27], v202 offset:13888
	ds_read_b128 v[28:31], v202 offset:13920
	s_waitcnt lgkmcnt(7)
	v_mfma_f32_32x32x16_bf16 v[158:173], v[0:3], v[48:51], v[236:251]
	s_waitcnt lgkmcnt(6)
	v_mfma_f32_32x32x16_bf16 v[158:173], v[4:7], v[52:55], v[158:173]
	s_waitcnt lgkmcnt(5)
	v_mfma_f32_32x32x16_bf16 v[158:173], v[8:11], v[56:59], v[158:173]
	s_waitcnt lgkmcnt(4)
	v_mfma_f32_32x32x16_bf16 v[158:173], v[12:15], v[60:63], v[158:173]
	ds_read_b128 v[0:3], v202 offset:18432
	ds_read_b128 v[4:7], v202 offset:18464
	ds_read_b128 v[8:11], v202 offset:18496
	ds_read_b128 v[12:15], v202 offset:18528
	s_waitcnt lgkmcnt(7)
	v_mfma_f32_32x32x16_bf16 v[204:219], v[16:19], v[48:51], v[236:251]
	s_waitcnt lgkmcnt(6)
	v_mfma_f32_32x32x16_bf16 v[204:219], v[20:23], v[52:55], v[204:219]
	s_waitcnt lgkmcnt(5)
	v_mfma_f32_32x32x16_bf16 v[204:219], v[24:27], v[56:59], v[204:219]
	s_waitcnt lgkmcnt(4)
	v_mfma_f32_32x32x16_bf16 v[204:219], v[28:31], v[60:63], v[204:219]
	s_waitcnt lgkmcnt(3)
	v_mfma_f32_32x32x16_bf16 v[220:235], v[0:3], v[48:51], v[236:251]
	s_waitcnt lgkmcnt(2)
	v_mfma_f32_32x32x16_bf16 v[220:235], v[4:7], v[52:55], v[220:235]
	s_waitcnt lgkmcnt(1)
	v_mfma_f32_32x32x16_bf16 v[220:235], v[8:11], v[56:59], v[220:235]
	s_waitcnt lgkmcnt(0)
	v_mfma_f32_32x32x16_bf16 v[220:235], v[12:15], v[60:63], v[220:235]
	s_nop 7
	s_nop 3
	v_cmp_lt_i32_e64 s[8:9], v188, 0
	v_cmp_lt_i32_e64 s[10:11], v188, 1
	v_cmp_lt_i32_e64 vcc, v188, 2
	v_cndmask_b32_e64 v220, v220, v200, s[8:9]
	v_cmp_lt_i32_e64 s[8:9], v188, 3
	v_cndmask_b32_e64 v221, v221, v200, s[10:11]
	v_cmp_lt_i32_e64 s[10:11], v188, 4
	v_cndmask_b32_e64 v222, v222, v200, vcc
	v_cmp_lt_i32_e64 vcc, v188, 5
	v_cndmask_b32_e64 v223, v223, v200, s[8:9]
	v_cmp_lt_i32_e64 s[8:9], v188, 6
	v_cndmask_b32_e64 v224, v224, v200, s[10:11]
	v_cmp_lt_i32_e64 s[10:11], v188, 7
	v_cndmask_b32_e64 v225, v225, v200, vcc
	v_cmp_lt_i32_e64 vcc, v188, 16
	v_cndmask_b32_e64 v226, v226, v200, s[8:9]
	v_cmp_lt_i32_e64 s[8:9], v188, 17
	v_cndmask_b32_e64 v227, v227, v200, s[10:11]
	v_cmp_lt_i32_e64 s[10:11], v188, 18
	v_cndmask_b32_e64 v228, v228, v200, vcc
	v_cmp_lt_i32_e64 vcc, v188, 19
	v_cndmask_b32_e64 v229, v229, v200, s[8:9]
	v_cmp_lt_i32_e64 s[8:9], v188, 20
	v_cndmask_b32_e64 v230, v230, v200, s[10:11]
	v_cmp_lt_i32_e64 s[10:11], v188, 21
	v_cndmask_b32_e64 v231, v231, v200, vcc
	v_cmp_lt_i32_e64 vcc, v188, 22
	v_cndmask_b32_e64 v232, v232, v200, s[8:9]
	v_cmp_lt_i32_e64 s[8:9], v188, 23
	s_nop 0
	v_cndmask_b32_e64 v233, v233, v200, s[10:11]
	v_cndmask_b32_e64 v234, v234, v200, vcc
	v_cndmask_b32_e64 v235, v235, v200, s[8:9]
	v_cmp_gt_i32_e64 s[8:9], v253, 0
	v_cmp_gt_i32_e64 s[10:11], v253, 1
	v_cmp_gt_i32_e64 vcc, v253, 2
	v_cndmask_b32_e64 v32, v32, v200, s[8:9]
	v_cmp_gt_i32_e64 s[8:9], v253, 3
	v_cndmask_b32_e64 v33, v33, v200, s[10:11]
	v_cmp_gt_i32_e64 s[10:11], v253, 4
	v_cndmask_b32_e64 v34, v34, v200, vcc
	v_cmp_gt_i32_e64 vcc, v253, 5
	v_cndmask_b32_e64 v35, v35, v200, s[8:9]
	v_cmp_gt_i32_e64 s[8:9], v253, 6
	v_cndmask_b32_e64 v36, v36, v200, s[10:11]
	v_cmp_gt_i32_e64 s[10:11], v253, 7
	v_cndmask_b32_e64 v37, v37, v200, vcc
	v_cmp_gt_i32_e64 vcc, v253, 16
	v_cndmask_b32_e64 v38, v38, v200, s[8:9]
	v_cmp_gt_i32_e64 s[8:9], v253, 17
	v_cndmask_b32_e64 v39, v39, v200, s[10:11]
	v_cmp_gt_i32_e64 s[10:11], v253, 18
	v_cndmask_b32_e64 v40, v40, v200, vcc
	v_cmp_gt_i32_e64 vcc, v253, 19
	v_cndmask_b32_e64 v41, v41, v200, s[8:9]
	v_cmp_gt_i32_e64 s[8:9], v253, 20
	v_cndmask_b32_e64 v42, v42, v200, s[10:11]
	v_cmp_gt_i32_e64 s[10:11], v253, 21
	v_cndmask_b32_e64 v43, v43, v200, vcc
	v_cmp_gt_i32_e64 vcc, v253, 22
	v_cndmask_b32_e64 v44, v44, v200, s[8:9]
	v_cmp_gt_i32_e64 s[8:9], v253, 23
	s_nop 0
	v_cndmask_b32_e64 v45, v45, v200, s[10:11]
	v_cndmask_b32_e64 v46, v46, v200, vcc
	v_cndmask_b32_e64 v47, v47, v200, s[8:9]
	s_cmpk_lt_i32 s14, 0x0
	s_cbranch_scc0 .Lat3_nn0
	v_mov_b32_e32 v32, v200
	v_mov_b32_e32 v33, v200
	v_mov_b32_e32 v34, v200
	v_mov_b32_e32 v35, v200
	v_mov_b32_e32 v36, v200
	v_mov_b32_e32 v37, v200
	v_mov_b32_e32 v38, v200
	v_mov_b32_e32 v39, v200
	v_mov_b32_e32 v40, v200
	v_mov_b32_e32 v41, v200
	v_mov_b32_e32 v42, v200
	v_mov_b32_e32 v43, v200
	v_mov_b32_e32 v44, v200
	v_mov_b32_e32 v45, v200
	v_mov_b32_e32 v46, v200
	v_mov_b32_e32 v47, v200
.Lat3_nn0:
	s_cmpk_lt_i32 s14, 0xffe0
	s_cbranch_scc0 .Lat3_nn1
	v_mov_b32_e32 v142, v200
	v_mov_b32_e32 v143, v200
	v_mov_b32_e32 v144, v200
	v_mov_b32_e32 v145, v200
	v_mov_b32_e32 v146, v200
	v_mov_b32_e32 v147, v200
	v_mov_b32_e32 v148, v200
	v_mov_b32_e32 v149, v200
	v_mov_b32_e32 v150, v200
	v_mov_b32_e32 v151, v200
	v_mov_b32_e32 v152, v200
	v_mov_b32_e32 v153, v200
	v_mov_b32_e32 v154, v200
	v_mov_b32_e32 v155, v200
	v_mov_b32_e32 v156, v200
	v_mov_b32_e32 v157, v200
.Lat3_nn1:
	s_cmpk_lt_i32 s14, 0xffc0
	s_cbranch_scc0 .Lat3_nn2
	v_mov_b32_e32 v158, v200
	v_mov_b32_e32 v159, v200
	v_mov_b32_e32 v160, v200
	v_mov_b32_e32 v161, v200
	v_mov_b32_e32 v162, v200
	v_mov_b32_e32 v163, v200
	v_mov_b32_e32 v164, v200
	v_mov_b32_e32 v165, v200
	v_mov_b32_e32 v166, v200
	v_mov_b32_e32 v167, v200
	v_mov_b32_e32 v168, v200
	v_mov_b32_e32 v169, v200
	v_mov_b32_e32 v170, v200
	v_mov_b32_e32 v171, v200
	v_mov_b32_e32 v172, v200
	v_mov_b32_e32 v173, v200
.Lat3_nn2:
	s_cmpk_lt_i32 s14, 0xffa0
	s_cbranch_scc0 .Lat3_nn3
	v_mov_b32_e32 v204, v200
	v_mov_b32_e32 v205, v200
	v_mov_b32_e32 v206, v200
	v_mov_b32_e32 v207, v200
	v_mov_b32_e32 v208, v200
	v_mov_b32_e32 v209, v200
	v_mov_b32_e32 v210, v200
	v_mov_b32_e32 v211, v200
	v_mov_b32_e32 v212, v200
	v_mov_b32_e32 v213, v200
	v_mov_b32_e32 v214, v200
	v_mov_b32_e32 v215, v200
	v_mov_b32_e32 v216, v200
	v_mov_b32_e32 v217, v200
	v_mov_b32_e32 v218, v200
	v_mov_b32_e32 v219, v200
.Lat3_nn3:
	v_max3_f32 v0, v32, v33, v34
	v_max3_f32 v1, v35, v36, v37
	v_max3_f32 v2, v38, v39, v40
	v_max3_f32 v3, v41, v42, v43
	v_max3_f32 v4, v44, v45, v46
	v_max3_f32 v5, v142, v143, v144
	v_max3_f32 v6, v145, v146, v147
	v_max3_f32 v7, v148, v149, v150
	v_max3_f32 v8, v151, v152, v153
	v_max3_f32 v9, v154, v155, v156
	v_max3_f32 v10, v158, v159, v160
	v_max3_f32 v11, v161, v162, v163
	v_max3_f32 v12, v164, v165, v166
	v_max3_f32 v13, v167, v168, v169
	v_max3_f32 v14, v170, v171, v172
	v_max3_f32 v15, v204, v205, v206
	v_max3_f32 v16, v207, v208, v209
	v_max3_f32 v17, v210, v211, v212
	v_max3_f32 v18, v213, v214, v215
	v_max3_f32 v19, v216, v217, v218
	v_max3_f32 v20, v220, v221, v222
	v_max3_f32 v21, v223, v224, v225
	v_max3_f32 v22, v226, v227, v228
	v_max3_f32 v23, v229, v230, v231
	v_max3_f32 v24, v232, v233, v234
	v_max3_f32 v0, v0, v1, v2
	v_max3_f32 v3, v3, v4, v47
	v_max3_f32 v5, v5, v6, v7
	v_max3_f32 v8, v8, v9, v157
	v_max3_f32 v10, v10, v11, v12
	v_max3_f32 v13, v13, v14, v173
	v_max3_f32 v15, v15, v16, v17
	v_max3_f32 v18, v18, v19, v219
	v_max3_f32 v20, v20, v21, v22
	v_max3_f32 v23, v23, v24, v235
	v_max_f32_e32 v0, v0, v3
	v_max_f32_e32 v5, v5, v8
	v_max_f32_e32 v10, v10, v13
	v_max_f32_e32 v15, v15, v18
	v_max_f32_e32 v20, v20, v23
	v_fma_f32 v5, v203, 1.0, v5
	v_fma_f32 v10, v203, 2.0, v10
	v_fma_f32 v20, v203, 4.0, v20
	v_fmamk_f32 v15, v203, 0x40400000, v15
	v_max3_f32 v0, v0, v5, v10
	v_max3_f32 v0, v0, v15, v20
	s_nop 0
	ds_bpermute_b32 v25, v141, v0
	s_waitcnt lgkmcnt(0)
	v_max3_f32 v174, v201, v0, v25
	v_sub_f32_e32 v90, v201, v174
	v_exp_f32_e32 v90, v90
	v_mov_b32_e32 v26, v174
	v_fma_f32 v27, -v203, 1.0, v174
	v_fma_f32 v28, -v203, 2.0, v174
	v_fma_f32 v30, -v203, 4.0, v174
	v_mul_f32_e32 v29, 0x40400000, v203
	v_sub_f32_e32 v29, v174, v29
	v_sub_f32_e32 v32, v32, v26
	v_sub_f32_e32 v33, v33, v26
	v_sub_f32_e32 v34, v34, v26
	v_sub_f32_e32 v35, v35, v26
	v_sub_f32_e32 v36, v36, v26
	v_sub_f32_e32 v37, v37, v26
	v_sub_f32_e32 v38, v38, v26
	v_sub_f32_e32 v39, v39, v26
	v_sub_f32_e32 v40, v40, v26
	v_sub_f32_e32 v41, v41, v26
	v_sub_f32_e32 v42, v42, v26
	v_sub_f32_e32 v43, v43, v26
	v_sub_f32_e32 v44, v44, v26
	v_sub_f32_e32 v45, v45, v26
	v_sub_f32_e32 v46, v46, v26
	v_sub_f32_e32 v47, v47, v26
	v_exp_f32_e32 v32, v32
	v_exp_f32_e32 v33, v33
	v_exp_f32_e32 v34, v34
	v_exp_f32_e32 v35, v35
	v_exp_f32_e32 v36, v36
	v_exp_f32_e32 v37, v37
	v_exp_f32_e32 v38, v38
	v_exp_f32_e32 v39, v39
	v_exp_f32_e32 v40, v40
	v_exp_f32_e32 v41, v41
	v_exp_f32_e32 v42, v42
	v_exp_f32_e32 v43, v43
	v_exp_f32_e32 v44, v44
	v_exp_f32_e32 v45, v45
	v_exp_f32_e32 v46, v46
	v_exp_f32_e32 v47, v47
	v_mov_b32_e32 v2, v32
	v_mov_b32_e32 v3, v33
	v_mov_b32_e32 v4, v34
	v_mov_b32_e32 v5, v35
	v_pk_add_f32 v[2:3], v[2:3], v[36:37]
	v_pk_add_f32 v[4:5], v[4:5], v[38:39]
	v_pk_add_f32 v[2:3], v[2:3], v[40:41]
	v_pk_add_f32 v[4:5], v[4:5], v[42:43]
	v_pk_add_f32 v[2:3], v[2:3], v[44:45]
	v_pk_add_f32 v[4:5], v[4:5], v[46:47]
	v_cvt_pk_bf16_f32 v32, v32, v33
	v_cvt_pk_bf16_f32 v33, v34, v35
	v_cvt_pk_bf16_f32 v34, v36, v37
	v_cvt_pk_bf16_f32 v35, v38, v39
	v_cvt_pk_bf16_f32 v36, v40, v41
	v_cvt_pk_bf16_f32 v37, v42, v43
	v_cvt_pk_bf16_f32 v38, v44, v45
	v_cvt_pk_bf16_f32 v39, v46, v47
	v_sub_f32_e32 v142, v142, v27
	v_sub_f32_e32 v143, v143, v27
	v_sub_f32_e32 v144, v144, v27
	v_sub_f32_e32 v145, v145, v27
	v_sub_f32_e32 v146, v146, v27
	v_sub_f32_e32 v147, v147, v27
	v_sub_f32_e32 v148, v148, v27
	v_sub_f32_e32 v149, v149, v27
	v_sub_f32_e32 v150, v150, v27
	v_sub_f32_e32 v151, v151, v27
	v_sub_f32_e32 v152, v152, v27
	v_sub_f32_e32 v153, v153, v27
	v_sub_f32_e32 v154, v154, v27
	v_sub_f32_e32 v155, v155, v27
	v_sub_f32_e32 v156, v156, v27
	v_sub_f32_e32 v157, v157, v27
	v_exp_f32_e32 v142, v142
	v_exp_f32_e32 v143, v143
	v_exp_f32_e32 v144, v144
	v_exp_f32_e32 v145, v145
	v_exp_f32_e32 v146, v146
	v_exp_f32_e32 v147, v147
	v_exp_f32_e32 v148, v148
	v_exp_f32_e32 v149, v149
	v_exp_f32_e32 v150, v150
	v_exp_f32_e32 v151, v151
	v_exp_f32_e32 v152, v152
	v_exp_f32_e32 v153, v153
	v_exp_f32_e32 v154, v154
	v_exp_f32_e32 v155, v155
	v_exp_f32_e32 v156, v156
	v_exp_f32_e32 v157, v157
	v_pk_add_f32 v[2:3], v[2:3], v[142:143]
	v_pk_add_f32 v[4:5], v[4:5], v[144:145]
	v_pk_add_f32 v[2:3], v[2:3], v[146:147]
	v_pk_add_f32 v[4:5], v[4:5], v[148:149]
	v_pk_add_f32 v[2:3], v[2:3], v[150:151]
	v_pk_add_f32 v[4:5], v[4:5], v[152:153]
	v_pk_add_f32 v[2:3], v[2:3], v[154:155]
	v_pk_add_f32 v[4:5], v[4:5], v[156:157]
	v_cvt_pk_bf16_f32 v142, v142, v143
	v_cvt_pk_bf16_f32 v143, v144, v145
	v_cvt_pk_bf16_f32 v144, v146, v147
	v_cvt_pk_bf16_f32 v145, v148, v149
	v_cvt_pk_bf16_f32 v146, v150, v151
	v_cvt_pk_bf16_f32 v147, v152, v153
	v_cvt_pk_bf16_f32 v148, v154, v155
	v_cvt_pk_bf16_f32 v149, v156, v157
	v_sub_f32_e32 v158, v158, v28
	v_sub_f32_e32 v159, v159, v28
	v_sub_f32_e32 v160, v160, v28
	v_sub_f32_e32 v161, v161, v28
	v_sub_f32_e32 v162, v162, v28
	v_sub_f32_e32 v163, v163, v28
	v_sub_f32_e32 v164, v164, v28
	v_sub_f32_e32 v165, v165, v28
	v_sub_f32_e32 v166, v166, v28
	v_sub_f32_e32 v167, v167, v28
	v_sub_f32_e32 v168, v168, v28
	v_sub_f32_e32 v169, v169, v28
	v_sub_f32_e32 v170, v170, v28
	v_sub_f32_e32 v171, v171, v28
	v_sub_f32_e32 v172, v172, v28
	v_sub_f32_e32 v173, v173, v28
	v_exp_f32_e32 v158, v158
	v_exp_f32_e32 v159, v159
	v_exp_f32_e32 v160, v160
	v_exp_f32_e32 v161, v161
	v_exp_f32_e32 v162, v162
	v_exp_f32_e32 v163, v163
	v_exp_f32_e32 v164, v164
	v_exp_f32_e32 v165, v165
	v_exp_f32_e32 v166, v166
	v_exp_f32_e32 v167, v167
	v_exp_f32_e32 v168, v168
	v_exp_f32_e32 v169, v169
	v_exp_f32_e32 v170, v170
	v_exp_f32_e32 v171, v171
	v_exp_f32_e32 v172, v172
	v_exp_f32_e32 v173, v173
	v_pk_add_f32 v[2:3], v[2:3], v[158:159]
	v_pk_add_f32 v[4:5], v[4:5], v[160:161]
	v_pk_add_f32 v[2:3], v[2:3], v[162:163]
	v_pk_add_f32 v[4:5], v[4:5], v[164:165]
	v_pk_add_f32 v[2:3], v[2:3], v[166:167]
	v_pk_add_f32 v[4:5], v[4:5], v[168:169]
	v_pk_add_f32 v[2:3], v[2:3], v[170:171]
	v_pk_add_f32 v[4:5], v[4:5], v[172:173]
	v_cvt_pk_bf16_f32 v158, v158, v159
	v_cvt_pk_bf16_f32 v159, v160, v161
	v_cvt_pk_bf16_f32 v160, v162, v163
	v_cvt_pk_bf16_f32 v161, v164, v165
	v_cvt_pk_bf16_f32 v162, v166, v167
	v_cvt_pk_bf16_f32 v163, v168, v169
	v_cvt_pk_bf16_f32 v164, v170, v171
	v_cvt_pk_bf16_f32 v165, v172, v173
	v_sub_f32_e32 v204, v204, v29
	v_sub_f32_e32 v205, v205, v29
	v_sub_f32_e32 v206, v206, v29
	v_sub_f32_e32 v207, v207, v29
	v_sub_f32_e32 v208, v208, v29
	v_sub_f32_e32 v209, v209, v29
	v_sub_f32_e32 v210, v210, v29
	v_sub_f32_e32 v211, v211, v29
	v_sub_f32_e32 v212, v212, v29
	v_sub_f32_e32 v213, v213, v29
	v_sub_f32_e32 v214, v214, v29
	v_sub_f32_e32 v215, v215, v29
	v_sub_f32_e32 v216, v216, v29
	v_sub_f32_e32 v217, v217, v29
	v_sub_f32_e32 v218, v218, v29
	v_sub_f32_e32 v219, v219, v29
	v_exp_f32_e32 v204, v204
	v_exp_f32_e32 v205, v205
	v_exp_f32_e32 v206, v206
	v_exp_f32_e32 v207, v207
	v_exp_f32_e32 v208, v208
	v_exp_f32_e32 v209, v209
	v_exp_f32_e32 v210, v210
	v_exp_f32_e32 v211, v211
	v_exp_f32_e32 v212, v212
	v_exp_f32_e32 v213, v213
	v_exp_f32_e32 v214, v214
	v_exp_f32_e32 v215, v215
	v_exp_f32_e32 v216, v216
	v_exp_f32_e32 v217, v217
	v_exp_f32_e32 v218, v218
	v_exp_f32_e32 v219, v219
	v_pk_add_f32 v[2:3], v[2:3], v[204:205]
	v_pk_add_f32 v[4:5], v[4:5], v[206:207]
	v_pk_add_f32 v[2:3], v[2:3], v[208:209]
	v_pk_add_f32 v[4:5], v[4:5], v[210:211]
	v_pk_add_f32 v[2:3], v[2:3], v[212:213]
	v_pk_add_f32 v[4:5], v[4:5], v[214:215]
	v_pk_add_f32 v[2:3], v[2:3], v[216:217]
	v_pk_add_f32 v[4:5], v[4:5], v[218:219]
	v_cvt_pk_bf16_f32 v204, v204, v205
	v_cvt_pk_bf16_f32 v205, v206, v207
	v_cvt_pk_bf16_f32 v206, v208, v209
	v_cvt_pk_bf16_f32 v207, v210, v211
	v_cvt_pk_bf16_f32 v208, v212, v213
	v_cvt_pk_bf16_f32 v209, v214, v215
	v_cvt_pk_bf16_f32 v210, v216, v217
	v_cvt_pk_bf16_f32 v211, v218, v219
	v_sub_f32_e32 v220, v220, v30
	v_sub_f32_e32 v221, v221, v30
	v_sub_f32_e32 v222, v222, v30
	v_sub_f32_e32 v223, v223, v30
	v_sub_f32_e32 v224, v224, v30
	v_sub_f32_e32 v225, v225, v30
	v_sub_f32_e32 v226, v226, v30
	v_sub_f32_e32 v227, v227, v30
	v_sub_f32_e32 v228, v228, v30
	v_sub_f32_e32 v229, v229, v30
	v_sub_f32_e32 v230, v230, v30
	v_sub_f32_e32 v231, v231, v30
	v_sub_f32_e32 v232, v232, v30
	v_sub_f32_e32 v233, v233, v30
	v_sub_f32_e32 v234, v234, v30
	v_sub_f32_e32 v235, v235, v30
	v_exp_f32_e32 v220, v220
	v_exp_f32_e32 v221, v221
	v_exp_f32_e32 v222, v222
	v_exp_f32_e32 v223, v223
	v_exp_f32_e32 v224, v224
	v_exp_f32_e32 v225, v225
	v_exp_f32_e32 v226, v226
	v_exp_f32_e32 v227, v227
	v_exp_f32_e32 v228, v228
	v_exp_f32_e32 v229, v229
	v_exp_f32_e32 v230, v230
	v_exp_f32_e32 v231, v231
	v_exp_f32_e32 v232, v232
	v_exp_f32_e32 v233, v233
	v_exp_f32_e32 v234, v234
	v_exp_f32_e32 v235, v235
	v_pk_add_f32 v[2:3], v[2:3], v[220:221]
	v_pk_add_f32 v[4:5], v[4:5], v[222:223]
	v_pk_add_f32 v[2:3], v[2:3], v[224:225]
	v_pk_add_f32 v[4:5], v[4:5], v[226:227]
	v_pk_add_f32 v[2:3], v[2:3], v[228:229]
	v_pk_add_f32 v[4:5], v[4:5], v[230:231]
	v_pk_add_f32 v[2:3], v[2:3], v[232:233]
	v_pk_add_f32 v[4:5], v[4:5], v[234:235]
	v_cvt_pk_bf16_f32 v220, v220, v221
	v_cvt_pk_bf16_f32 v221, v222, v223
	v_cvt_pk_bf16_f32 v222, v224, v225
	v_cvt_pk_bf16_f32 v223, v226, v227
	v_cvt_pk_bf16_f32 v224, v228, v229
	v_cvt_pk_bf16_f32 v225, v230, v231
	v_cvt_pk_bf16_f32 v226, v232, v233
	v_cvt_pk_bf16_f32 v227, v234, v235
	s_nop 1
	ds_read_b64_tr_b16 v[40:41], v252
	ds_read_b64_tr_b16 v[42:43], v252 offset:576
	ds_read_b64_tr_b16 v[44:45], v252 offset:64
	ds_read_b64_tr_b16 v[46:47], v252 offset:640
	ds_read_b64_tr_b16 v[150:151], v252 offset:2304
	ds_read_b64_tr_b16 v[152:153], v252 offset:2880
	ds_read_b64_tr_b16 v[154:155], v252 offset:2368
	ds_read_b64_tr_b16 v[156:157], v252 offset:2944
	v_pk_add_f32 v[2:3], v[2:3], v[4:5]
	s_nop 0
	v_add_f32_e32 v175, v2, v3
	v_fmac_f32_e32 v175, v89, v90
	s_waitcnt lgkmcnt(6)
	v_mfma_f32_32x32x16_bf16 v[0:15], v[40:43], v[32:35], 0
	s_waitcnt lgkmcnt(4)
	v_mfma_f32_32x32x16_bf16 v[16:31], v[44:47], v[32:35], 0
	ds_read_b64_tr_b16 v[40:41], v252 offset:4608
	ds_read_b64_tr_b16 v[42:43], v252 offset:5184
	ds_read_b64_tr_b16 v[44:45], v252 offset:4672
	ds_read_b64_tr_b16 v[46:47], v252 offset:5248
	s_waitcnt lgkmcnt(6)
	v_mfma_f32_32x32x16_bf16 v[0:15], v[150:153], v[36:39], v[0:15]
	s_waitcnt lgkmcnt(4)
	v_mfma_f32_32x32x16_bf16 v[16:31], v[154:157], v[36:39], v[16:31]
	ds_read_b64_tr_b16 v[150:151], v252 offset:6912
	ds_read_b64_tr_b16 v[152:153], v252 offset:7488
	ds_read_b64_tr_b16 v[154:155], v252 offset:6976
	ds_read_b64_tr_b16 v[156:157], v252 offset:7552
	s_waitcnt lgkmcnt(6)
	v_mfma_f32_32x32x16_bf16 v[0:15], v[40:43], v[142:145], v[0:15]
	s_waitcnt lgkmcnt(4)
	v_mfma_f32_32x32x16_bf16 v[16:31], v[44:47], v[142:145], v[16:31]
	ds_read_b64_tr_b16 v[40:41], v252 offset:9216
	ds_read_b64_tr_b16 v[42:43], v252 offset:9792
	ds_read_b64_tr_b16 v[44:45], v252 offset:9280
	ds_read_b64_tr_b16 v[46:47], v252 offset:9856
	s_waitcnt lgkmcnt(6)
	v_mfma_f32_32x32x16_bf16 v[0:15], v[150:153], v[146:149], v[0:15]
	s_waitcnt lgkmcnt(4)
	v_mfma_f32_32x32x16_bf16 v[16:31], v[154:157], v[146:149], v[16:31]
	ds_read_b64_tr_b16 v[150:151], v252 offset:11520
	ds_read_b64_tr_b16 v[152:153], v252 offset:12096
	ds_read_b64_tr_b16 v[154:155], v252 offset:11584
	ds_read_b64_tr_b16 v[156:157], v252 offset:12160
	s_waitcnt lgkmcnt(6)
	v_mfma_f32_32x32x16_bf16 v[0:15], v[40:43], v[158:161], v[0:15]
	s_waitcnt lgkmcnt(4)
	v_mfma_f32_32x32x16_bf16 v[16:31], v[44:47], v[158:161], v[16:31]
	ds_read_b64_tr_b16 v[40:41], v252 offset:13824
	ds_read_b64_tr_b16 v[42:43], v252 offset:14400
	ds_read_b64_tr_b16 v[44:45], v252 offset:13888
	ds_read_b64_tr_b16 v[46:47], v252 offset:14464
	s_waitcnt lgkmcnt(6)
	v_mfma_f32_32x32x16_bf16 v[0:15], v[150:153], v[162:165], v[0:15]
	s_waitcnt lgkmcnt(4)
	v_mfma_f32_32x32x16_bf16 v[16:31], v[154:157], v[162:165], v[16:31]
	ds_read_b64_tr_b16 v[150:151], v252 offset:16128
	ds_read_b64_tr_b16 v[152:153], v252 offset:16704
	ds_read_b64_tr_b16 v[154:155], v252 offset:16192
	ds_read_b64_tr_b16 v[156:157], v252 offset:16768
	s_waitcnt lgkmcnt(6)
	v_mfma_f32_32x32x16_bf16 v[0:15], v[40:43], v[204:207], v[0:15]
	s_waitcnt lgkmcnt(4)
	v_mfma_f32_32x32x16_bf16 v[16:31], v[44:47], v[204:207], v[16:31]
	ds_read_b64_tr_b16 v[40:41], v252 offset:18432
	ds_read_b64_tr_b16 v[42:43], v252 offset:19008
	ds_read_b64_tr_b16 v[44:45], v252 offset:18496
	ds_read_b64_tr_b16 v[46:47], v252 offset:19072
	s_waitcnt lgkmcnt(6)
	v_mfma_f32_32x32x16_bf16 v[0:15], v[150:153], v[208:211], v[0:15]
	s_waitcnt lgkmcnt(4)
	v_mfma_f32_32x32x16_bf16 v[16:31], v[154:157], v[208:211], v[16:31]
	ds_read_b64_tr_b16 v[150:151], v252 offset:20736
	ds_read_b64_tr_b16 v[152:153], v252 offset:21312
	ds_read_b64_tr_b16 v[154:155], v252 offset:20800
	ds_read_b64_tr_b16 v[156:157], v252 offset:21376
	s_waitcnt lgkmcnt(6)
	v_mfma_f32_32x32x16_bf16 v[0:15], v[40:43], v[220:223], v[0:15]
	s_waitcnt lgkmcnt(4)
	v_mfma_f32_32x32x16_bf16 v[16:31], v[44:47], v[220:223], v[16:31]
	s_waitcnt lgkmcnt(2)
	v_mfma_f32_32x32x16_bf16 v[0:15], v[150:153], v[224:227], v[0:15]
	s_waitcnt lgkmcnt(0)
	v_mfma_f32_32x32x16_bf16 v[16:31], v[154:157], v[224:227], v[16:31]
	v_mov_b32_e32 v37, v174
	v_mov_b32_e32 v38, v175

.LBB0_1280:
	s_add_i32 s5, s81, 1
	v_cvt_f32_i32_e32 v1, s5
	s_sub_i32 s5, 0x80, s67
	v_add_u32_e32 v253, s5, v188
	v_mul_f32_e32 v1, 0xc1000000, v1
	v_div_scale_f32 v2, s[10:11], s34, s34, v1
	v_rcp_f32_e32 v3, v2
	v_div_scale_f32 v4, vcc, v1, s34, v1
	s_mov_b32 s10, 0xc2fc0000
	v_fma_f32 v5, -v2, v3, 1.0
	v_fmac_f32_e32 v3, v5, v3
	v_mul_f32_e32 v5, v4, v3
	v_fma_f32 v6, -v2, v5, v4
	v_fmac_f32_e32 v5, v6, v3
	v_fma_f32 v2, -v2, v5, v4
	v_div_fmas_f32 v2, v2, v3, v5
	v_div_fixup_f32 v1, v2, s34, v1
	v_cmp_gt_f32_e32 vcc, s10, v1
	s_and_b64 s[10:11], vcc, exec
	s_cselect_b32 s10, 0xffffffc0, 0
	v_cndmask_b32_e32 v2, 0, v198, vcc
	v_add_f32_e32 v1, v1, v2
	v_exp_f32_e32 v1, v1
	v_cvt_f32_u32_e32 v2, s1
	v_and_b32_e32 v3, 64, v199
	v_add_u32_e32 v3, 64, v3
	v_ldexp_f32 v1, v1, s10
	v_mul_f32_e32 v1, v1, v2
	v_xor_b32_e32 v2, 32, v199
	v_mul_f32_e32 v91, 0x3fb8aa3b, v1
	v_add_u32_e32 v1, s7, v189
	v_cmp_lt_i32_e32 vcc, v2, v3
	v_subrev_u32_e32 v1, s79, v1
	v_mad_u32_u24 v252, v1, s71, v138
	v_cndmask_b32_e32 v2, v199, v2, vcc
	v_add_u32_e32 v1, s7, v190
	v_lshlrev_b32_e32 v141, 2, v2
	v_subrev_u32_e32 v1, s79, v1
	v_mad_u32_u24 v202, v1, s71, v132
	v_add_u32_e32 v252, 0xd800, v252
	s_add_i32 s14, s7, 0xffffff80
	ds_read_b128 v[0:3], v202
	ds_read_b128 v[4:7], v202 offset:32
	ds_read_b128 v[8:11], v202 offset:64
	ds_read_b128 v[12:15], v202 offset:96
	ds_read_b128 v[16:19], v202 offset:4608
	ds_read_b128 v[20:23], v202 offset:4640
	ds_read_b128 v[24:27], v202 offset:4672
	ds_read_b128 v[28:31], v202 offset:4704
	v_add_u32_e32 v174, 0x80, v188
	v_cvt_f32_i32_e32 v174, v174
	v_mul_f32_e64 v174, -v91, v174
	v_mul_f32_e32 v203, 0x42000000, v91
	v_fmamk_f32 v236, v91, 0x00000000, v174
	v_fmamk_f32 v237, v91, 0x3f800000, v174
	v_fmamk_f32 v238, v91, 0x40000000, v174
	v_fmamk_f32 v239, v91, 0x40400000, v174
	v_fmamk_f32 v240, v91, 0x40800000, v174
	v_fmamk_f32 v241, v91, 0x40a00000, v174
	v_fmamk_f32 v242, v91, 0x40c00000, v174
	v_fmamk_f32 v243, v91, 0x40e00000, v174
	v_fmamk_f32 v244, v91, 0x41800000, v174
	v_fmamk_f32 v245, v91, 0x41880000, v174
	v_fmamk_f32 v246, v91, 0x41900000, v174
	v_fmamk_f32 v247, v91, 0x41980000, v174
	v_fmamk_f32 v248, v91, 0x41a00000, v174
	v_fmamk_f32 v249, v91, 0x41a80000, v174
	v_fmamk_f32 v250, v91, 0x41b00000, v174
	v_fmamk_f32 v251, v91, 0x41b80000, v174
	s_nop 1
	s_waitcnt lgkmcnt(7)
	v_mfma_f32_32x32x16_bf16 v[32:47], v[0:3], v[48:51], v[236:251]
	s_waitcnt lgkmcnt(6)
	v_mfma_f32_32x32x16_bf16 v[32:47], v[4:7], v[52:55], v[32:47]
	s_waitcnt lgkmcnt(5)
	v_mfma_f32_32x32x16_bf16 v[32:47], v[8:11], v[56:59], v[32:47]
	s_waitcnt lgkmcnt(4)
	v_mfma_f32_32x32x16_bf16 v[32:47], v[12:15], v[60:63], v[32:47]
	ds_read_b128 v[0:3], v202 offset:9216
	ds_read_b128 v[4:7], v202 offset:9248
	ds_read_b128 v[8:11], v202 offset:9280
	ds_read_b128 v[12:15], v202 offset:9312
	s_waitcnt lgkmcnt(7)
	v_mfma_f32_32x32x16_bf16 v[142:157], v[16:19], v[48:51], v[236:251]
	s_waitcnt lgkmcnt(6)
	v_mfma_f32_32x32x16_bf16 v[142:157], v[20:23], v[52:55], v[142:157]
	s_waitcnt lgkmcnt(5)
	v_mfma_f32_32x32x16_bf16 v[142:157], v[24:27], v[56:59], v[142:157]
	s_waitcnt lgkmcnt(4)
	v_mfma_f32_32x32x16_bf16 v[142:157], v[28:31], v[60:63], v[142:157]
	ds_read_b128 v[16:19], v202 offset:13824
	ds_read_b128 v[20:23], v202 offset:13856
	ds_read_b128 v[24:27], v202 offset:13888
	ds_read_b128 v[28:31], v202 offset:13920
	s_waitcnt lgkmcnt(7)
	v_mfma_f32_32x32x16_bf16 v[158:173], v[0:3], v[48:51], v[236:251]
	s_waitcnt lgkmcnt(6)
	v_mfma_f32_32x32x16_bf16 v[158:173], v[4:7], v[52:55], v[158:173]
	s_waitcnt lgkmcnt(5)
	v_mfma_f32_32x32x16_bf16 v[158:173], v[8:11], v[56:59], v[158:173]
	s_waitcnt lgkmcnt(4)
	v_mfma_f32_32x32x16_bf16 v[158:173], v[12:15], v[60:63], v[158:173]
	ds_read_b128 v[0:3], v202 offset:18432
	ds_read_b128 v[4:7], v202 offset:18464
	ds_read_b128 v[8:11], v202 offset:18496
	ds_read_b128 v[12:15], v202 offset:18528
	s_waitcnt lgkmcnt(7)
	v_mfma_f32_32x32x16_bf16 v[204:219], v[16:19], v[48:51], v[236:251]
	s_waitcnt lgkmcnt(6)
	v_mfma_f32_32x32x16_bf16 v[204:219], v[20:23], v[52:55], v[204:219]
	s_waitcnt lgkmcnt(5)
	v_mfma_f32_32x32x16_bf16 v[204:219], v[24:27], v[56:59], v[204:219]
	s_waitcnt lgkmcnt(4)
	v_mfma_f32_32x32x16_bf16 v[204:219], v[28:31], v[60:63], v[204:219]
	s_waitcnt lgkmcnt(3)
	v_mfma_f32_32x32x16_bf16 v[220:235], v[0:3], v[48:51], v[236:251]
	s_waitcnt lgkmcnt(2)
	v_mfma_f32_32x32x16_bf16 v[220:235], v[4:7], v[52:55], v[220:235]
	s_waitcnt lgkmcnt(1)
	v_mfma_f32_32x32x16_bf16 v[220:235], v[8:11], v[56:59], v[220:235]
	s_waitcnt lgkmcnt(0)
	v_mfma_f32_32x32x16_bf16 v[220:235], v[12:15], v[60:63], v[220:235]
	s_nop 7
	s_nop 3
	v_cmp_lt_i32_e64 s[10:11], v188, 0
	v_cmp_lt_i32_e64 s[12:13], v188, 1
	v_cmp_lt_i32_e64 vcc, v188, 2
	v_cndmask_b32_e64 v220, v220, v200, s[10:11]
	v_cmp_lt_i32_e64 s[10:11], v188, 3
	v_cndmask_b32_e64 v221, v221, v200, s[12:13]
	v_cmp_lt_i32_e64 s[12:13], v188, 4
	v_cndmask_b32_e64 v222, v222, v200, vcc
	v_cmp_lt_i32_e64 vcc, v188, 5
	v_cndmask_b32_e64 v223, v223, v200, s[10:11]
	v_cmp_lt_i32_e64 s[10:11], v188, 6
	v_cndmask_b32_e64 v224, v224, v200, s[12:13]
	v_cmp_lt_i32_e64 s[12:13], v188, 7
	v_cndmask_b32_e64 v225, v225, v200, vcc
	v_cmp_lt_i32_e64 vcc, v188, 16
	v_cndmask_b32_e64 v226, v226, v200, s[10:11]
	v_cmp_lt_i32_e64 s[10:11], v188, 17
	v_cndmask_b32_e64 v227, v227, v200, s[12:13]
	v_cmp_lt_i32_e64 s[12:13], v188, 18
	v_cndmask_b32_e64 v228, v228, v200, vcc
	v_cmp_lt_i32_e64 vcc, v188, 19
	v_cndmask_b32_e64 v229, v229, v200, s[10:11]
	v_cmp_lt_i32_e64 s[10:11], v188, 20
	v_cndmask_b32_e64 v230, v230, v200, s[12:13]
	v_cmp_lt_i32_e64 s[12:13], v188, 21
	v_cndmask_b32_e64 v231, v231, v200, vcc
	v_cmp_lt_i32_e64 vcc, v188, 22
	v_cndmask_b32_e64 v232, v232, v200, s[10:11]
	v_cmp_lt_i32_e64 s[10:11], v188, 23
	s_nop 0
	v_cndmask_b32_e64 v233, v233, v200, s[12:13]
	v_cndmask_b32_e64 v234, v234, v200, vcc
	v_cndmask_b32_e64 v235, v235, v200, s[10:11]
	v_cmp_gt_i32_e64 s[10:11], v253, 0
	v_cmp_gt_i32_e64 s[12:13], v253, 1
	v_cmp_gt_i32_e64 vcc, v253, 2
	v_cndmask_b32_e64 v32, v32, v200, s[10:11]
	v_cmp_gt_i32_e64 s[10:11], v253, 3
	v_cndmask_b32_e64 v33, v33, v200, s[12:13]
	v_cmp_gt_i32_e64 s[12:13], v253, 4
	v_cndmask_b32_e64 v34, v34, v200, vcc
	v_cmp_gt_i32_e64 vcc, v253, 5
	v_cndmask_b32_e64 v35, v35, v200, s[10:11]
	v_cmp_gt_i32_e64 s[10:11], v253, 6
	v_cndmask_b32_e64 v36, v36, v200, s[12:13]
	v_cmp_gt_i32_e64 s[12:13], v253, 7
	v_cndmask_b32_e64 v37, v37, v200, vcc
	v_cmp_gt_i32_e64 vcc, v253, 16
	v_cndmask_b32_e64 v38, v38, v200, s[10:11]
	v_cmp_gt_i32_e64 s[10:11], v253, 17
	v_cndmask_b32_e64 v39, v39, v200, s[12:13]
	v_cmp_gt_i32_e64 s[12:13], v253, 18
	v_cndmask_b32_e64 v40, v40, v200, vcc
	v_cmp_gt_i32_e64 vcc, v253, 19
	v_cndmask_b32_e64 v41, v41, v200, s[10:11]
	v_cmp_gt_i32_e64 s[10:11], v253, 20
	v_cndmask_b32_e64 v42, v42, v200, s[12:13]
	v_cmp_gt_i32_e64 s[12:13], v253, 21
	v_cndmask_b32_e64 v43, v43, v200, vcc
	v_cmp_gt_i32_e64 vcc, v253, 22
	v_cndmask_b32_e64 v44, v44, v200, s[10:11]
	v_cmp_gt_i32_e64 s[10:11], v253, 23
	s_nop 0
	v_cndmask_b32_e64 v45, v45, v200, s[12:13]
	v_cndmask_b32_e64 v46, v46, v200, vcc
	v_cndmask_b32_e64 v47, v47, v200, s[10:11]
	s_cmpk_lt_i32 s14, 0x0
	s_cbranch_scc0 .Lat11_nn0
	v_mov_b32_e32 v32, v200
	v_mov_b32_e32 v33, v200
	v_mov_b32_e32 v34, v200
	v_mov_b32_e32 v35, v200
	v_mov_b32_e32 v36, v200
	v_mov_b32_e32 v37, v200
	v_mov_b32_e32 v38, v200
	v_mov_b32_e32 v39, v200
	v_mov_b32_e32 v40, v200
	v_mov_b32_e32 v41, v200
	v_mov_b32_e32 v42, v200
	v_mov_b32_e32 v43, v200
	v_mov_b32_e32 v44, v200
	v_mov_b32_e32 v45, v200
	v_mov_b32_e32 v46, v200
	v_mov_b32_e32 v47, v200

.LBB0_2140:
	s_add_i32 s5, s81, 1
	v_cvt_f32_i32_e32 v1, s5
	s_sub_i32 s5, 0x80, s67
	v_add_u32_e32 v253, s5, v188
	v_mul_f32_e32 v1, 0xc1000000, v1
	v_div_scale_f32 v2, s[12:13], s34, s34, v1
	v_rcp_f32_e32 v3, v2
	v_div_scale_f32 v4, vcc, v1, s34, v1
	s_mov_b32 s12, 0xc2fc0000
	v_fma_f32 v5, -v2, v3, 1.0
	v_fmac_f32_e32 v3, v5, v3
	v_mul_f32_e32 v5, v4, v3
	v_fma_f32 v6, -v2, v5, v4
	v_fmac_f32_e32 v5, v6, v3
	v_fma_f32 v2, -v2, v5, v4
	v_div_fmas_f32 v2, v2, v3, v5
	v_div_fixup_f32 v1, v2, s34, v1
	v_cmp_gt_f32_e32 vcc, s12, v1
	s_and_b64 s[12:13], vcc, exec
	s_cselect_b32 s12, 0xffffffc0, 0
	v_cndmask_b32_e32 v2, 0, v198, vcc
	v_add_f32_e32 v1, v1, v2
	v_exp_f32_e32 v1, v1
	v_cvt_f32_u32_e32 v2, s1
	v_and_b32_e32 v3, 64, v199
	v_add_u32_e32 v3, 64, v3
	v_ldexp_f32 v1, v1, s12
	v_mul_f32_e32 v1, v1, v2
	v_xor_b32_e32 v2, 32, v199
	v_mul_f32_e32 v91, 0x3fb8aa3b, v1
	v_add_u32_e32 v1, s7, v189
	v_cmp_lt_i32_e32 vcc, v2, v3
	v_subrev_u32_e32 v1, s93, v1
	v_mad_u32_u24 v252, v1, s71, v138
	v_cndmask_b32_e32 v2, v199, v2, vcc
	v_add_u32_e32 v1, s7, v190
	v_lshlrev_b32_e32 v141, 2, v2
	v_subrev_u32_e32 v1, s93, v1
	v_mad_u32_u24 v202, v1, s71, v132
	v_add_u32_e32 v252, 0xd800, v252
	s_add_i32 s8, s7, 0xffffff80
	ds_read_b128 v[0:3], v202
	ds_read_b128 v[4:7], v202 offset:32
	ds_read_b128 v[8:11], v202 offset:64
	ds_read_b128 v[12:15], v202 offset:96
	ds_read_b128 v[16:19], v202 offset:4608
	ds_read_b128 v[20:23], v202 offset:4640
	ds_read_b128 v[24:27], v202 offset:4672
	ds_read_b128 v[28:31], v202 offset:4704
	v_add_u32_e32 v174, 0x80, v188
	v_cvt_f32_i32_e32 v174, v174
	v_mul_f32_e64 v174, -v91, v174
	v_mul_f32_e32 v203, 0x42000000, v91
	v_fmamk_f32 v236, v91, 0x00000000, v174
	v_fmamk_f32 v237, v91, 0x3f800000, v174
	v_fmamk_f32 v238, v91, 0x40000000, v174
	v_fmamk_f32 v239, v91, 0x40400000, v174
	v_fmamk_f32 v240, v91, 0x40800000, v174
	v_fmamk_f32 v241, v91, 0x40a00000, v174
	v_fmamk_f32 v242, v91, 0x40c00000, v174
	v_fmamk_f32 v243, v91, 0x40e00000, v174
	v_fmamk_f32 v244, v91, 0x41800000, v174
	v_fmamk_f32 v245, v91, 0x41880000, v174
	v_fmamk_f32 v246, v91, 0x41900000, v174
	v_fmamk_f32 v247, v91, 0x41980000, v174
	v_fmamk_f32 v248, v91, 0x41a00000, v174
	v_fmamk_f32 v249, v91, 0x41a80000, v174
	v_fmamk_f32 v250, v91, 0x41b00000, v174
	v_fmamk_f32 v251, v91, 0x41b80000, v174
	s_nop 1
	s_waitcnt lgkmcnt(7)
	v_mfma_f32_32x32x16_bf16 v[32:47], v[0:3], v[48:51], v[236:251]
	s_waitcnt lgkmcnt(6)
	v_mfma_f32_32x32x16_bf16 v[32:47], v[4:7], v[52:55], v[32:47]
	s_waitcnt lgkmcnt(5)
	v_mfma_f32_32x32x16_bf16 v[32:47], v[8:11], v[56:59], v[32:47]
	s_waitcnt lgkmcnt(4)
	v_mfma_f32_32x32x16_bf16 v[32:47], v[12:15], v[60:63], v[32:47]
	ds_read_b128 v[0:3], v202 offset:9216
	ds_read_b128 v[4:7], v202 offset:9248
	ds_read_b128 v[8:11], v202 offset:9280
	ds_read_b128 v[12:15], v202 offset:9312
	s_waitcnt lgkmcnt(7)
	v_mfma_f32_32x32x16_bf16 v[142:157], v[16:19], v[48:51], v[236:251]
	s_waitcnt lgkmcnt(6)
	v_mfma_f32_32x32x16_bf16 v[142:157], v[20:23], v[52:55], v[142:157]
	s_waitcnt lgkmcnt(5)
	v_mfma_f32_32x32x16_bf16 v[142:157], v[24:27], v[56:59], v[142:157]
	s_waitcnt lgkmcnt(4)
	v_mfma_f32_32x32x16_bf16 v[142:157], v[28:31], v[60:63], v[142:157]
	ds_read_b128 v[16:19], v202 offset:13824
	ds_read_b128 v[20:23], v202 offset:13856
	ds_read_b128 v[24:27], v202 offset:13888
	ds_read_b128 v[28:31], v202 offset:13920
	s_waitcnt lgkmcnt(7)
	v_mfma_f32_32x32x16_bf16 v[158:173], v[0:3], v[48:51], v[236:251]
	s_waitcnt lgkmcnt(6)
	v_mfma_f32_32x32x16_bf16 v[158:173], v[4:7], v[52:55], v[158:173]
	s_waitcnt lgkmcnt(5)
	v_mfma_f32_32x32x16_bf16 v[158:173], v[8:11], v[56:59], v[158:173]
	s_waitcnt lgkmcnt(4)
	v_mfma_f32_32x32x16_bf16 v[158:173], v[12:15], v[60:63], v[158:173]
	ds_read_b128 v[0:3], v202 offset:18432
	ds_read_b128 v[4:7], v202 offset:18464
	ds_read_b128 v[8:11], v202 offset:18496
	ds_read_b128 v[12:15], v202 offset:18528
	s_waitcnt lgkmcnt(7)
	v_mfma_f32_32x32x16_bf16 v[204:219], v[16:19], v[48:51], v[236:251]
	s_waitcnt lgkmcnt(6)
	v_mfma_f32_32x32x16_bf16 v[204:219], v[20:23], v[52:55], v[204:219]
	s_waitcnt lgkmcnt(5)
	v_mfma_f32_32x32x16_bf16 v[204:219], v[24:27], v[56:59], v[204:219]
	s_waitcnt lgkmcnt(4)
	v_mfma_f32_32x32x16_bf16 v[204:219], v[28:31], v[60:63], v[204:219]
	s_waitcnt lgkmcnt(3)
	v_mfma_f32_32x32x16_bf16 v[220:235], v[0:3], v[48:51], v[236:251]
	s_waitcnt lgkmcnt(2)
	v_mfma_f32_32x32x16_bf16 v[220:235], v[4:7], v[52:55], v[220:235]
	s_waitcnt lgkmcnt(1)
	v_mfma_f32_32x32x16_bf16 v[220:235], v[8:11], v[56:59], v[220:235]
	s_waitcnt lgkmcnt(0)
	v_mfma_f32_32x32x16_bf16 v[220:235], v[12:15], v[60:63], v[220:235]
	s_nop 7
	s_nop 3
	v_cmp_lt_i32_e64 s[12:13], v188, 0
	v_cmp_lt_i32_e64 s[14:15], v188, 1
	v_cmp_lt_i32_e64 vcc, v188, 2
	v_cndmask_b32_e64 v220, v220, v200, s[12:13]
	v_cmp_lt_i32_e64 s[12:13], v188, 3
	v_cndmask_b32_e64 v221, v221, v200, s[14:15]
	v_cmp_lt_i32_e64 s[14:15], v188, 4
	v_cndmask_b32_e64 v222, v222, v200, vcc
	v_cmp_lt_i32_e64 vcc, v188, 5
	v_cndmask_b32_e64 v223, v223, v200, s[12:13]
	v_cmp_lt_i32_e64 s[12:13], v188, 6
	v_cndmask_b32_e64 v224, v224, v200, s[14:15]
	v_cmp_lt_i32_e64 s[14:15], v188, 7
	v_cndmask_b32_e64 v225, v225, v200, vcc
	v_cmp_lt_i32_e64 vcc, v188, 16
	v_cndmask_b32_e64 v226, v226, v200, s[12:13]
	v_cmp_lt_i32_e64 s[12:13], v188, 17
	v_cndmask_b32_e64 v227, v227, v200, s[14:15]
	v_cmp_lt_i32_e64 s[14:15], v188, 18
	v_cndmask_b32_e64 v228, v228, v200, vcc
	v_cmp_lt_i32_e64 vcc, v188, 19
	v_cndmask_b32_e64 v229, v229, v200, s[12:13]
	v_cmp_lt_i32_e64 s[12:13], v188, 20
	v_cndmask_b32_e64 v230, v230, v200, s[14:15]
	v_cmp_lt_i32_e64 s[14:15], v188, 21
	v_cndmask_b32_e64 v231, v231, v200, vcc
	v_cmp_lt_i32_e64 vcc, v188, 22
	v_cndmask_b32_e64 v232, v232, v200, s[12:13]
	v_cmp_lt_i32_e64 s[12:13], v188, 23
	s_nop 0
	v_cndmask_b32_e64 v233, v233, v200, s[14:15]
	v_cndmask_b32_e64 v234, v234, v200, vcc
	v_cndmask_b32_e64 v235, v235, v200, s[12:13]
	v_cmp_gt_i32_e64 s[12:13], v253, 0
	v_cmp_gt_i32_e64 s[14:15], v253, 1
	v_cmp_gt_i32_e64 vcc, v253, 2
	v_cndmask_b32_e64 v32, v32, v200, s[12:13]
	v_cmp_gt_i32_e64 s[12:13], v253, 3
	v_cndmask_b32_e64 v33, v33, v200, s[14:15]
	v_cmp_gt_i32_e64 s[14:15], v253, 4
	v_cndmask_b32_e64 v34, v34, v200, vcc
	v_cmp_gt_i32_e64 vcc, v253, 5
	v_cndmask_b32_e64 v35, v35, v200, s[12:13]
	v_cmp_gt_i32_e64 s[12:13], v253, 6
	v_cndmask_b32_e64 v36, v36, v200, s[14:15]
	v_cmp_gt_i32_e64 s[14:15], v253, 7
	v_cndmask_b32_e64 v37, v37, v200, vcc
	v_cmp_gt_i32_e64 vcc, v253, 16
	v_cndmask_b32_e64 v38, v38, v200, s[12:13]
	v_cmp_gt_i32_e64 s[12:13], v253, 17
	v_cndmask_b32_e64 v39, v39, v200, s[14:15]
	v_cmp_gt_i32_e64 s[14:15], v253, 18
	v_cndmask_b32_e64 v40, v40, v200, vcc
	v_cmp_gt_i32_e64 vcc, v253, 19
	v_cndmask_b32_e64 v41, v41, v200, s[12:13]
	v_cmp_gt_i32_e64 s[12:13], v253, 20
	v_cndmask_b32_e64 v42, v42, v200, s[14:15]
	v_cmp_gt_i32_e64 s[14:15], v253, 21
	v_cndmask_b32_e64 v43, v43, v200, vcc
	v_cmp_gt_i32_e64 vcc, v253, 22
	v_cndmask_b32_e64 v44, v44, v200, s[12:13]
	v_cmp_gt_i32_e64 s[12:13], v253, 23
	s_nop 0
	v_cndmask_b32_e64 v45, v45, v200, s[14:15]
	v_cndmask_b32_e64 v46, v46, v200, vcc
	v_cndmask_b32_e64 v47, v47, v200, s[12:13]
	s_cmpk_lt_i32 s8, 0x0
	s_cbranch_scc0 .Lat19_nn0
	v_mov_b32_e32 v32, v200
	v_mov_b32_e32 v33, v200
	v_mov_b32_e32 v34, v200
	v_mov_b32_e32 v35, v200
	v_mov_b32_e32 v36, v200
	v_mov_b32_e32 v37, v200
	v_mov_b32_e32 v38, v200
	v_mov_b32_e32 v39, v200
	v_mov_b32_e32 v40, v200
	v_mov_b32_e32 v41, v200
	v_mov_b32_e32 v42, v200
	v_mov_b32_e32 v43, v200
	v_mov_b32_e32 v44, v200
	v_mov_b32_e32 v45, v200
	v_mov_b32_e32 v46, v200
	v_mov_b32_e32 v47, v200
.Lat19_nn0:
	s_cmpk_lt_i32 s8, 0xffe0
	s_cbranch_scc0 .Lat19_nn1
	v_mov_b32_e32 v142, v200
	v_mov_b32_e32 v143, v200
	v_mov_b32_e32 v144, v200
	v_mov_b32_e32 v145, v200
	v_mov_b32_e32 v146, v200
	v_mov_b32_e32 v147, v200
	v_mov_b32_e32 v148, v200
	v_mov_b32_e32 v149, v200
	v_mov_b32_e32 v150, v200
	v_mov_b32_e32 v151, v200
	v_mov_b32_e32 v152, v200
	v_mov_b32_e32 v153, v200
	v_mov_b32_e32 v154, v200
	v_mov_b32_e32 v155, v200
	v_mov_b32_e32 v156, v200
	v_mov_b32_e32 v157, v200
.Lat19_nn1:
	s_cmpk_lt_i32 s8, 0xffc0
	s_cbranch_scc0 .Lat19_nn2
	v_mov_b32_e32 v158, v200
	v_mov_b32_e32 v159, v200
	v_mov_b32_e32 v160, v200
	v_mov_b32_e32 v161, v200
	v_mov_b32_e32 v162, v200
	v_mov_b32_e32 v163, v200
	v_mov_b32_e32 v164, v200
	v_mov_b32_e32 v165, v200
	v_mov_b32_e32 v166, v200
	v_mov_b32_e32 v167, v200
	v_mov_b32_e32 v168, v200
	v_mov_b32_e32 v169, v200
	v_mov_b32_e32 v170, v200
	v_mov_b32_e32 v171, v200
	v_mov_b32_e32 v172, v200
	v_mov_b32_e32 v173, v200
.Lat19_nn2:
	s_cmpk_lt_i32 s8, 0xffa0
	s_cbranch_scc0 .Lat19_nn3
	v_mov_b32_e32 v204, v200
	v_mov_b32_e32 v205, v200
	v_mov_b32_e32 v206, v200
	v_mov_b32_e32 v207, v200
	v_mov_b32_e32 v208, v200
	v_mov_b32_e32 v209, v200
	v_mov_b32_e32 v210, v200
	v_mov_b32_e32 v211, v200
	v_mov_b32_e32 v212, v200
	v_mov_b32_e32 v213, v200
	v_mov_b32_e32 v214, v200
	v_mov_b32_e32 v215, v200
	v_mov_b32_e32 v216, v200
	v_mov_b32_e32 v217, v200
	v_mov_b32_e32 v218, v200
	v_mov_b32_e32 v219, v200

.LBB0_3004:
	s_add_i32 s5, s82, 1
	v_cvt_f32_i32_e32 v1, s5
	s_sub_i32 s5, 0x80, s55
	v_add_u32_e32 v253, s5, v188
	v_mul_f32_e32 v1, 0xc1000000, v1
	v_div_scale_f32 v2, s[10:11], s18, s18, v1
	v_rcp_f32_e32 v3, v2
	v_div_scale_f32 v4, vcc, v1, s18, v1
	s_mov_b32 s10, 0xc2fc0000
	v_fma_f32 v5, -v2, v3, 1.0
	v_fmac_f32_e32 v3, v5, v3
	v_mul_f32_e32 v5, v4, v3
	v_fma_f32 v6, -v2, v5, v4
	v_fmac_f32_e32 v5, v6, v3
	v_fma_f32 v2, -v2, v5, v4
	v_div_fmas_f32 v2, v2, v3, v5
	v_div_fixup_f32 v1, v2, s18, v1
	v_cmp_gt_f32_e32 vcc, s10, v1
	s_and_b64 s[10:11], vcc, exec
	s_cselect_b32 s10, 0xffffffc0, 0
	v_cndmask_b32_e32 v2, 0, v198, vcc
	v_add_f32_e32 v1, v1, v2
	v_exp_f32_e32 v1, v1
	v_cvt_f32_u32_e32 v2, s1
	v_and_b32_e32 v3, 64, v199
	v_add_u32_e32 v3, 64, v3
	v_ldexp_f32 v1, v1, s10
	v_mul_f32_e32 v1, v1, v2
	v_xor_b32_e32 v2, 32, v199
	v_mul_f32_e32 v91, 0x3fb8aa3b, v1
	v_add_u32_e32 v1, s9, v189
	v_cmp_lt_i32_e32 vcc, v2, v3
	v_subrev_u32_e32 v1, s81, v1
	v_mad_u32_u24 v252, v1, s65, v138
	v_cndmask_b32_e32 v2, v199, v2, vcc
	v_add_u32_e32 v1, s9, v190
	v_lshlrev_b32_e32 v141, 2, v2
	v_subrev_u32_e32 v1, s81, v1
	v_mad_u32_u24 v202, v1, s65, v132
	v_add_u32_e32 v252, 0xd800, v252
	s_add_i32 s16, s9, 0xffffff80
	ds_read_b128 v[0:3], v202
	ds_read_b128 v[4:7], v202 offset:32
	ds_read_b128 v[8:11], v202 offset:64
	ds_read_b128 v[12:15], v202 offset:96
	ds_read_b128 v[16:19], v202 offset:4608
	ds_read_b128 v[20:23], v202 offset:4640
	ds_read_b128 v[24:27], v202 offset:4672
	ds_read_b128 v[28:31], v202 offset:4704
	v_add_u32_e32 v174, 0x80, v188
	v_cvt_f32_i32_e32 v174, v174
	v_mul_f32_e64 v174, -v91, v174
	v_mul_f32_e32 v203, 0x42000000, v91
	v_fmamk_f32 v236, v91, 0x00000000, v174
	v_fmamk_f32 v237, v91, 0x3f800000, v174
	v_fmamk_f32 v238, v91, 0x40000000, v174
	v_fmamk_f32 v239, v91, 0x40400000, v174
	v_fmamk_f32 v240, v91, 0x40800000, v174
	v_fmamk_f32 v241, v91, 0x40a00000, v174
	v_fmamk_f32 v242, v91, 0x40c00000, v174
	v_fmamk_f32 v243, v91, 0x40e00000, v174
	v_fmamk_f32 v244, v91, 0x41800000, v174
	v_fmamk_f32 v245, v91, 0x41880000, v174
	v_fmamk_f32 v246, v91, 0x41900000, v174
	v_fmamk_f32 v247, v91, 0x41980000, v174
	v_fmamk_f32 v248, v91, 0x41a00000, v174
	v_fmamk_f32 v249, v91, 0x41a80000, v174
	v_fmamk_f32 v250, v91, 0x41b00000, v174
	v_fmamk_f32 v251, v91, 0x41b80000, v174
	s_nop 1
	s_waitcnt lgkmcnt(7)
	v_mfma_f32_32x32x16_bf16 v[32:47], v[0:3], v[48:51], v[236:251]
	s_waitcnt lgkmcnt(6)
	v_mfma_f32_32x32x16_bf16 v[32:47], v[4:7], v[52:55], v[32:47]
	s_waitcnt lgkmcnt(5)
	v_mfma_f32_32x32x16_bf16 v[32:47], v[8:11], v[56:59], v[32:47]
	s_waitcnt lgkmcnt(4)
	v_mfma_f32_32x32x16_bf16 v[32:47], v[12:15], v[60:63], v[32:47]
	ds_read_b128 v[0:3], v202 offset:9216
	ds_read_b128 v[4:7], v202 offset:9248
	ds_read_b128 v[8:11], v202 offset:9280
	ds_read_b128 v[12:15], v202 offset:9312
	s_waitcnt lgkmcnt(7)
	v_mfma_f32_32x32x16_bf16 v[142:157], v[16:19], v[48:51], v[236:251]
	s_waitcnt lgkmcnt(6)
	v_mfma_f32_32x32x16_bf16 v[142:157], v[20:23], v[52:55], v[142:157]
	s_waitcnt lgkmcnt(5)
	v_mfma_f32_32x32x16_bf16 v[142:157], v[24:27], v[56:59], v[142:157]
	s_waitcnt lgkmcnt(4)
	v_mfma_f32_32x32x16_bf16 v[142:157], v[28:31], v[60:63], v[142:157]
	ds_read_b128 v[16:19], v202 offset:13824
	ds_read_b128 v[20:23], v202 offset:13856
	ds_read_b128 v[24:27], v202 offset:13888
	ds_read_b128 v[28:31], v202 offset:13920
	s_waitcnt lgkmcnt(7)
	v_mfma_f32_32x32x16_bf16 v[158:173], v[0:3], v[48:51], v[236:251]
	s_waitcnt lgkmcnt(6)
	v_mfma_f32_32x32x16_bf16 v[158:173], v[4:7], v[52:55], v[158:173]
	s_waitcnt lgkmcnt(5)
	v_mfma_f32_32x32x16_bf16 v[158:173], v[8:11], v[56:59], v[158:173]
	s_waitcnt lgkmcnt(4)
	v_mfma_f32_32x32x16_bf16 v[158:173], v[12:15], v[60:63], v[158:173]
	ds_read_b128 v[0:3], v202 offset:18432
	ds_read_b128 v[4:7], v202 offset:18464
	ds_read_b128 v[8:11], v202 offset:18496
	ds_read_b128 v[12:15], v202 offset:18528
	s_waitcnt lgkmcnt(7)
	v_mfma_f32_32x32x16_bf16 v[204:219], v[16:19], v[48:51], v[236:251]
	s_waitcnt lgkmcnt(6)
	v_mfma_f32_32x32x16_bf16 v[204:219], v[20:23], v[52:55], v[204:219]
	s_waitcnt lgkmcnt(5)
	v_mfma_f32_32x32x16_bf16 v[204:219], v[24:27], v[56:59], v[204:219]
	s_waitcnt lgkmcnt(4)
	v_mfma_f32_32x32x16_bf16 v[204:219], v[28:31], v[60:63], v[204:219]
	s_waitcnt lgkmcnt(3)
	v_mfma_f32_32x32x16_bf16 v[220:235], v[0:3], v[48:51], v[236:251]
	s_waitcnt lgkmcnt(2)
	v_mfma_f32_32x32x16_bf16 v[220:235], v[4:7], v[52:55], v[220:235]
	s_waitcnt lgkmcnt(1)
	v_mfma_f32_32x32x16_bf16 v[220:235], v[8:11], v[56:59], v[220:235]
	s_waitcnt lgkmcnt(0)
	v_mfma_f32_32x32x16_bf16 v[220:235], v[12:15], v[60:63], v[220:235]
	s_nop 7
	s_nop 3
	v_cmp_lt_i32_e64 s[10:11], v188, 0
	v_cmp_lt_i32_e64 s[12:13], v188, 1
	v_cmp_lt_i32_e64 vcc, v188, 2
	v_cndmask_b32_e64 v220, v220, v200, s[10:11]
	v_cmp_lt_i32_e64 s[10:11], v188, 3
	v_cndmask_b32_e64 v221, v221, v200, s[12:13]
	v_cmp_lt_i32_e64 s[12:13], v188, 4
	v_cndmask_b32_e64 v222, v222, v200, vcc
	v_cmp_lt_i32_e64 vcc, v188, 5
	v_cndmask_b32_e64 v223, v223, v200, s[10:11]
	v_cmp_lt_i32_e64 s[10:11], v188, 6
	v_cndmask_b32_e64 v224, v224, v200, s[12:13]
	v_cmp_lt_i32_e64 s[12:13], v188, 7
	v_cndmask_b32_e64 v225, v225, v200, vcc
	v_cmp_lt_i32_e64 vcc, v188, 16
	v_cndmask_b32_e64 v226, v226, v200, s[10:11]
	v_cmp_lt_i32_e64 s[10:11], v188, 17
	v_cndmask_b32_e64 v227, v227, v200, s[12:13]
	v_cmp_lt_i32_e64 s[12:13], v188, 18
	v_cndmask_b32_e64 v228, v228, v200, vcc
	v_cmp_lt_i32_e64 vcc, v188, 19
	v_cndmask_b32_e64 v229, v229, v200, s[10:11]
	v_cmp_lt_i32_e64 s[10:11], v188, 20
	v_cndmask_b32_e64 v230, v230, v200, s[12:13]
	v_cmp_lt_i32_e64 s[12:13], v188, 21
	v_cndmask_b32_e64 v231, v231, v200, vcc
	v_cmp_lt_i32_e64 vcc, v188, 22
	v_cndmask_b32_e64 v232, v232, v200, s[10:11]
	v_cmp_lt_i32_e64 s[10:11], v188, 23
	s_nop 0
	v_cndmask_b32_e64 v233, v233, v200, s[12:13]
	v_cndmask_b32_e64 v234, v234, v200, vcc
	v_cndmask_b32_e64 v235, v235, v200, s[10:11]
	v_cmp_gt_i32_e64 s[10:11], v253, 0
	v_cmp_gt_i32_e64 s[12:13], v253, 1
	v_cmp_gt_i32_e64 vcc, v253, 2
	v_cndmask_b32_e64 v32, v32, v200, s[10:11]
	v_cmp_gt_i32_e64 s[10:11], v253, 3
	v_cndmask_b32_e64 v33, v33, v200, s[12:13]
	v_cmp_gt_i32_e64 s[12:13], v253, 4
	v_cndmask_b32_e64 v34, v34, v200, vcc
	v_cmp_gt_i32_e64 vcc, v253, 5
	v_cndmask_b32_e64 v35, v35, v200, s[10:11]
	v_cmp_gt_i32_e64 s[10:11], v253, 6
	v_cndmask_b32_e64 v36, v36, v200, s[12:13]
	v_cmp_gt_i32_e64 s[12:13], v253, 7
	v_cndmask_b32_e64 v37, v37, v200, vcc
	v_cmp_gt_i32_e64 vcc, v253, 16
	v_cndmask_b32_e64 v38, v38, v200, s[10:11]
	v_cmp_gt_i32_e64 s[10:11], v253, 17
	v_cndmask_b32_e64 v39, v39, v200, s[12:13]
	v_cmp_gt_i32_e64 s[12:13], v253, 18
	v_cndmask_b32_e64 v40, v40, v200, vcc
	v_cmp_gt_i32_e64 vcc, v253, 19
	v_cndmask_b32_e64 v41, v41, v200, s[10:11]
	v_cmp_gt_i32_e64 s[10:11], v253, 20
	v_cndmask_b32_e64 v42, v42, v200, s[12:13]
	v_cmp_gt_i32_e64 s[12:13], v253, 21
	v_cndmask_b32_e64 v43, v43, v200, vcc
	v_cmp_gt_i32_e64 vcc, v253, 22
	v_cndmask_b32_e64 v44, v44, v200, s[10:11]
	v_cmp_gt_i32_e64 s[10:11], v253, 23
	s_nop 0
	v_cndmask_b32_e64 v45, v45, v200, s[12:13]
	v_cndmask_b32_e64 v46, v46, v200, vcc
	v_cndmask_b32_e64 v47, v47, v200, s[10:11]
	s_cmpk_lt_i32 s16, 0x0
	s_cbranch_scc0 .Lat27_nn0
	v_mov_b32_e32 v32, v200
	v_mov_b32_e32 v33, v200
	v_mov_b32_e32 v34, v200
	v_mov_b32_e32 v35, v200
	v_mov_b32_e32 v36, v200
	v_mov_b32_e32 v37, v200
	v_mov_b32_e32 v38, v200
	v_mov_b32_e32 v39, v200
	v_mov_b32_e32 v40, v200
	v_mov_b32_e32 v41, v200
	v_mov_b32_e32 v42, v200
	v_mov_b32_e32 v43, v200
	v_mov_b32_e32 v44, v200
	v_mov_b32_e32 v45, v200
	v_mov_b32_e32 v46, v200
	v_mov_b32_e32 v47, v200
.Lat27_nn0:
	s_cmpk_lt_i32 s16, 0xffe0
	s_cbranch_scc0 .Lat27_nn1
	v_mov_b32_e32 v142, v200
	v_mov_b32_e32 v143, v200
	v_mov_b32_e32 v144, v200
	v_mov_b32_e32 v145, v200
	v_mov_b32_e32 v146, v200
	v_mov_b32_e32 v147, v200
	v_mov_b32_e32 v148, v200
	v_mov_b32_e32 v149, v200
	v_mov_b32_e32 v150, v200
	v_mov_b32_e32 v151, v200
	v_mov_b32_e32 v152, v200
	v_mov_b32_e32 v153, v200
	v_mov_b32_e32 v154, v200
	v_mov_b32_e32 v155, v200
	v_mov_b32_e32 v156, v200
	v_mov_b32_e32 v157, v200
.Lat27_nn1:
	s_cmpk_lt_i32 s16, 0xffc0
	s_cbranch_scc0 .Lat27_nn2
	v_mov_b32_e32 v158, v200
	v_mov_b32_e32 v159, v200
	v_mov_b32_e32 v160, v200
	v_mov_b32_e32 v161, v200
	v_mov_b32_e32 v162, v200
	v_mov_b32_e32 v163, v200
	v_mov_b32_e32 v164, v200
	v_mov_b32_e32 v165, v200
	v_mov_b32_e32 v166, v200
	v_mov_b32_e32 v167, v200
	v_mov_b32_e32 v168, v200
	v_mov_b32_e32 v169, v200
	v_mov_b32_e32 v170, v200
	v_mov_b32_e32 v171, v200
	v_mov_b32_e32 v172, v200
	v_mov_b32_e32 v173, v200
.Lat27_nn2:
	s_cmpk_lt_i32 s16, 0xffa0
	s_cbranch_scc0 .Lat27_nn3
	v_mov_b32_e32 v204, v200
	v_mov_b32_e32 v205, v200
	v_mov_b32_e32 v206, v200
	v_mov_b32_e32 v207, v200
	v_mov_b32_e32 v208, v200
	v_mov_b32_e32 v209, v200
	v_mov_b32_e32 v210, v200
	v_mov_b32_e32 v211, v200
	v_mov_b32_e32 v212, v200
	v_mov_b32_e32 v213, v200
	v_mov_b32_e32 v214, v200
	v_mov_b32_e32 v215, v200
	v_mov_b32_e32 v216, v200
	v_mov_b32_e32 v217, v200
	v_mov_b32_e32 v218, v200
	v_mov_b32_e32 v219, v200
